# v20 plus: no-op vmcnt waits and stale s_nop removed; dense layer-0 loop next-tile loads unconditional (ladder and skip branch deleted, SCC exit test)
# speedup vs baseline: 1.0211x; 1.0081x over previous
; #define SBAR() __builtin_amdgcn_sched_barrier(0)
; #define SLOAD(i, k0) do { st_[i].vs = *reinterpret_cast<const bf16x8*>(&Vh[(size_t)((k0) + sr) * LDK + sc]); \
;     st_[i].ks = *reinterpret_cast<const bf16x8*>(&Kh[(size_t)((k0) + sr) * LDK + sc]); \
;     if (DQ == 96) st_[i].kr = *reinterpret_cast<const bf16x8*>(&Kr[(size_t)((k0) + sr2) * 32 + sc2]); } while (0)
; #define SWRITE(b, i) do { *(bf16x8*)(V_lds + (b) * SHM_V + vst0) = st_[i].vs; *(bf16x8*)(K_lds + (b) * SHM_K + kst0) = st_[i].ks; \
;     if (DQ == 96) { if (tid < 256) *(bf16x8*)(K_lds + (b) * SHM_K + kst2) = st_[i].kr; } } while (0)
; #define SWAIT() do { if (DQ == 96) asm volatile("s_waitcnt vmcnt(3)" ::: "memory"); else asm volatile("s_waitcnt vmcnt(2)" ::: "memory"); } while (0)
; #define SLOAD(i, k0) do { st_[i].vs = *reinterpret_cast<const bf16x8*>(&Vh[(size_t)((k0) + sr) * LDK + sc]); \
;     st_[i].ks = *reinterpret_cast<const bf16x8*>(&Kh[(size_t)((k0) + sr) * LDK + sc]); \
;     if (DQ == 96) st_[i].kr = *reinterpret_cast<const bf16x8*>(&Kr[(size_t)((k0) + sr2) * 32 + sc2]); } while (0)
; #define SWRITE(b, i) do { *(bf16x8*)(V_lds + (b) * SHM_V + vst0) = st_[i].vs; *(bf16x8*)(K_lds + (b) * SHM_K + kst0) = st_[i].ks; \
;     if (DQ == 96) { if (tid < 256) *(bf16x8*)(K_lds + (b) * SHM_K + kst2) = st_[i].kr; } } while (0)
; #define SWAIT() do { if (DQ == 96) asm volatile("s_waitcnt vmcnt(3)" ::: "memory"); else asm volatile("s_waitcnt vmcnt(2)" ::: "memory"); } while (0)
; template <int DQ, bool WIN, int LDQ, int LDK> ...
;     ...
;     for (int j = 1; j + 1 < NT; j += 2) {
;         SBAR(); qkt<DQ>(pB0, pB1, K_lds + SHM_K, qr, minit, r32, hi);
;         finish(pA0, pA1); SBAR();
;         SLOAD(SO, KBASE(j + 2)); SBAR();
;         pv(vb0);
;         __syncthreads(); SWAIT(); SWRITE(0, SE);
;         lsum_upd();
;         if (WIN) win_mask(pB0, pB1, qrow - KBASE(j), hi);
;         exp16(pB0);
;         __syncthreads();
;         SBAR(); qkt<DQ>(pA0, pA1, K_lds, qr, minit, r32, hi);
;         finish(pB0, pB1); SBAR();
;         if (j + 3 < NT) SLOAD(SE, KBASE(j + 3)); SBAR();
;         pv(vb0 + SHM_V);
;         __syncthreads(); SWAIT(); SWRITE(1, SO);
;         lsum_upd();
;         if (WIN) win_mask(pA0, pA1, qrow - KBASE(j + 1), hi);
;         exp16(pA0);
;         __syncthreads();
.LBB0_492:
	ds_read_b64_tr_b16 v[168:169], v155 offset:0x1000
	ds_read_b64_tr_b16 v[170:171], v155 offset:0x1400
	ds_read_b64_tr_b16 v[172:173], v155 offset:0x1800
	ds_read_b64_tr_b16 v[174:175], v155 offset:0x1c00
	ds_read_b64_tr_b16 v[160:161], v155 offset:0x200
	ds_read_b64_tr_b16 v[162:163], v155 offset:0x600
	ds_read_b64_tr_b16 v[164:165], v155 offset:0xa00
	ds_read_b64_tr_b16 v[166:167], v155 offset:0xe00
	v_mfma_f32_32x32x16_bf16 v[2:17], v[94:97], v[42:45], v[2:17]
	v_mfma_f32_32x32x16_bf16 v[2:17], v[90:93], v[46:49], v[2:17]
	s_waitcnt lgkmcnt(6)
	v_mfma_f32_32x32x16_bf16 v[2:17], v[86:89], v[168:171], v[2:17]
	ds_read_b64_tr_b16 v[168:169], v155 offset:0x1200
	ds_read_b64_tr_b16 v[170:171], v155 offset:0x1600
	s_waitcnt lgkmcnt(6)
	v_mfma_f32_32x32x16_bf16 v[2:17], v[82:85], v[172:175], v[2:17]
	ds_read_b64_tr_b16 v[176:177], v155 offset:0x1a00
	ds_read_b64_tr_b16 v[178:179], v155 offset:0x1e00
	s_waitcnt lgkmcnt(0)
	v_mfma_f32_32x32x16_bf16 v[18:33], v[94:97], v[160:163], v[18:33]
	s_waitcnt vmcnt(2)
	ds_write_b128 v158, v[138:141] offset:8192
	ds_write_b128 v157, v[142:145] offset:25600
	v_exp_f32_e32 v138, v98
	v_exp_f32_e32 v139, v99
	v_mfma_f32_32x32x16_bf16 v[18:33], v[90:93], v[164:167], v[18:33]
	v_exp_f32_e32 v162, v100
	v_exp_f32_e32 v165, v101
	v_exp_f32_e32 v163, v102
	v_exp_f32_e32 v166, v103
	v_exp_f32_e32 v164, v104
	v_exp_f32_e32 v167, v105
	v_exp_f32_e32 v140, v106
	v_mfma_f32_32x32x16_bf16 v[18:33], v[86:89], v[168:171], v[18:33]
	v_exp_f32_e32 v144, v107
	v_exp_f32_e32 v141, v108
	v_exp_f32_e32 v145, v109
	v_exp_f32_e32 v142, v110
	v_exp_f32_e32 v160, v111
	v_mfma_f32_16x16x32_bf16 v[34:37], v[94:97], v[38:41], v[34:37]
	v_exp_f32_e32 v143, v112
	v_exp_f32_e32 v161, v113
	v_lshl_add_u64 v[148:149], v[148:149], 0, s[18:19]
	s_waitcnt lgkmcnt(0)
	s_barrier
	v_mfma_f32_16x16x32_bf16 v[34:37], v[90:93], v[38:41], v[34:37]
	v_mfma_f32_16x16x32_bf16 v[34:37], v[86:89], v[38:41], v[34:37]
	v_mfma_f32_32x32x16_bf16 v[18:33], v[82:85], v[176:179], v[18:33]
	v_mfma_f32_16x16x32_bf16 v[34:37], v[82:85], v[38:41], v[34:37]
	v_xor_b32_e32 v158, 0xc000, v158
	v_xor_b32_e32 v159, 0xc000, v159
	v_xor_b32_e32 v155, 0xc000, v155
	s_cmpk_gt_u32 s21, 0x7c
	s_cbranch_scc1 .LBB0_495
.LBB0_493:
	s_add_i32 s21, s21, 2
	ds_read_b64_tr_b16 v[42:43], v159 offset:0
	ds_read_b64_tr_b16 v[44:45], v159 offset:0x400
	ds_read_b64_tr_b16 v[46:47], v159 offset:0x800
	ds_read_b64_tr_b16 v[48:49], v159 offset:0xc00
	ds_read_b128 v[82:85], v156 offset:25600
	ds_read_b128 v[168:171], v156 offset:25632
	ds_read_b128 v[172:175], v156 offset:30208
	ds_read_b128 v[176:179], v156 offset:30240
	v_exp_f32_e32 v81, v81
	v_exp_f32_e32 v146, v66
	s_waitcnt lgkmcnt(3)
	v_mfma_f32_32x32x16_bf16 v[98:113], v[82:85], v[126:129], v[50:65]
	v_exp_f32_e32 v180, v67
	v_exp_f32_e32 v190, v68
	v_exp_f32_e32 v191, v73
	v_exp_f32_e32 v192, v74
	v_exp_f32_e32 v193, v75
	v_exp_f32_e32 v194, v80
	s_waitcnt lgkmcnt(1)
	v_mfma_f32_32x32x16_bf16 v[82:97], v[172:175], v[126:129], v[50:65]
	v_mfma_f32_32x32x16_bf16 v[98:113], v[168:171], v[122:125], v[98:113]
	ds_read_b128 v[168:171], v156 offset:25664
	ds_read_b128 v[172:175], v156 offset:25696
	ds_read_b128 v[182:185], v156 offset:30272
	ds_read_b128 v[186:189], v156 offset:30304
	v_cvt_pk_bf16_f32 v66, v138, v139
	v_cvt_pk_bf16_f32 v67, v162, v165
	v_cvt_pk_bf16_f32 v68, v163, v166
	s_waitcnt lgkmcnt(4)
	v_mfma_f32_32x32x16_bf16 v[82:97], v[176:179], v[122:125], v[82:97]
	v_exp_f32_e32 v176, v69
	v_exp_f32_e32 v177, v70
	v_exp_f32_e32 v178, v71
	v_exp_f32_e32 v179, v72
	v_cvt_pk_bf16_f32 v69, v164, v167
	v_cvt_pk_bf16_f32 v70, v140, v144
	v_cvt_pk_bf16_f32 v71, v141, v145
	s_waitcnt lgkmcnt(3)
	v_mfma_f32_32x32x16_bf16 v[98:113], v[168:171], v[118:121], v[98:113]
	v_exp_f32_e32 v168, v76
	v_exp_f32_e32 v169, v77
	v_exp_f32_e32 v170, v78
	v_exp_f32_e32 v171, v79
	v_cvt_pk_bf16_f32 v72, v142, v160
	v_cvt_pk_bf16_f32 v73, v143, v161
	v_cvt_pk_bf16_f32 v74, v146, v180
	s_waitcnt lgkmcnt(1)
	v_mfma_f32_32x32x16_bf16 v[82:97], v[182:185], v[118:121], v[82:97]
	v_cvt_pk_bf16_f32 v75, v190, v176
	v_cvt_pk_bf16_f32 v76, v177, v178
	v_cvt_pk_bf16_f32 v77, v179, v191
	v_cvt_pk_bf16_f32 v78, v192, v193
	v_cvt_pk_bf16_f32 v79, v168, v169
	v_cvt_pk_bf16_f32 v80, v170, v171
	v_cvt_pk_bf16_f32 v81, v194, v81
	v_mfma_f32_32x32x16_bf16 v[98:113], v[172:175], v[114:117], v[98:113]
	s_waitcnt lgkmcnt(0)
	v_mfma_f32_32x32x16_bf16 v[82:97], v[186:189], v[114:117], v[82:97]
	v_add_co_u32_e32 v142, vcc, s90, v148
	s_nop 1
	v_addc_co_u32_e32 v143, vcc, -1, v149, vcc
	global_load_dwordx4 v[138:141], v[142:143], off
	s_nop 0
	global_load_dwordx4 v[142:145], v[142:143], off offset:-256
	ds_read_b64_tr_b16 v[168:169], v159 offset:0x1000
	ds_read_b64_tr_b16 v[170:171], v159 offset:0x1400
	ds_read_b64_tr_b16 v[172:173], v159 offset:0x1800
	ds_read_b64_tr_b16 v[174:175], v159 offset:0x1c00
	ds_read_b64_tr_b16 v[160:161], v159 offset:0x200
	ds_read_b64_tr_b16 v[162:163], v159 offset:0x600
	ds_read_b64_tr_b16 v[164:165], v159 offset:0xa00
	ds_read_b64_tr_b16 v[166:167], v159 offset:0xe00
	v_mfma_f32_32x32x16_bf16 v[2:17], v[66:69], v[42:45], v[2:17]
	v_mfma_f32_32x32x16_bf16 v[2:17], v[70:73], v[46:49], v[2:17]
	s_waitcnt lgkmcnt(6)
	v_mfma_f32_32x32x16_bf16 v[2:17], v[74:77], v[168:171], v[2:17]
	ds_read_b64_tr_b16 v[168:169], v159 offset:0x1200
	ds_read_b64_tr_b16 v[170:171], v159 offset:0x1600
	s_waitcnt lgkmcnt(6)
	v_mfma_f32_32x32x16_bf16 v[2:17], v[78:81], v[172:175], v[2:17]
	ds_read_b64_tr_b16 v[176:177], v159 offset:0x1a00
	ds_read_b64_tr_b16 v[178:179], v159 offset:0x1e00
	s_waitcnt lgkmcnt(0)
	v_mfma_f32_32x32x16_bf16 v[18:33], v[66:69], v[160:163], v[18:33]
	s_waitcnt vmcnt(2)
	ds_write_b128 v158, v[134:137]
	ds_write_b128 v157, v[130:133] offset:16384
	v_mfma_f32_16x16x32_bf16 v[34:37], v[66:69], v[38:41], v[34:37]
	v_exp_f32_e32 v146, v98
	v_exp_f32_e32 v180, v99
	v_exp_f32_e32 v182, v100
	v_exp_f32_e32 v183, v101
	v_exp_f32_e32 v184, v102
	v_exp_f32_e32 v185, v103
	v_exp_f32_e32 v186, v104
	v_mfma_f32_32x32x16_bf16 v[18:33], v[70:73], v[164:167], v[18:33]
	v_exp_f32_e32 v187, v105
	v_exp_f32_e32 v188, v106
	v_exp_f32_e32 v189, v107
	v_exp_f32_e32 v190, v108
	v_exp_f32_e32 v191, v109
	v_exp_f32_e32 v192, v110
	v_exp_f32_e32 v193, v111
	v_mfma_f32_16x16x32_bf16 v[34:37], v[70:73], v[38:41], v[34:37]
	v_exp_f32_e32 v194, v112
	v_exp_f32_e32 v195, v113
	s_waitcnt lgkmcnt(0)
	s_barrier
; #define SBAR() __builtin_amdgcn_sched_barrier(0)
; #define SLOAD(i, k0) do { st_[i].vs = *reinterpret_cast<const bf16x8*>(&Vh[(size_t)((k0) + sr) * LDK + sc]); \
;     st_[i].ks = *reinterpret_cast<const bf16x8*>(&Kh[(size_t)((k0) + sr) * LDK + sc]); \
;     if (DQ == 96) st_[i].kr = *reinterpret_cast<const bf16x8*>(&Kr[(size_t)((k0) + sr2) * 32 + sc2]); } while (0)
; #define SWRITE(b, i) do { *(bf16x8*)(V_lds + (b) * SHM_V + vst0) = st_[i].vs; *(bf16x8*)(K_lds + (b) * SHM_K + kst0) = st_[i].ks; \
;     if (DQ == 96) { if (tid < 256) *(bf16x8*)(K_lds + (b) * SHM_K + kst2) = st_[i].kr; } } while (0)
; #define SWAIT() do { if (DQ == 96) asm volatile("s_waitcnt vmcnt(3)" ::: "memory"); else asm volatile("s_waitcnt vmcnt(2)" ::: "memory"); } while (0)
; #define SLOAD(i, k0) do { st_[i].vs = *reinterpret_cast<const bf16x8*>(&Vh[(size_t)((k0) + sr) * LDK + sc]); \
;     st_[i].ks = *reinterpret_cast<const bf16x8*>(&Kh[(size_t)((k0) + sr) * LDK + sc]); \
;     if (DQ == 96) st_[i].kr = *reinterpret_cast<const bf16x8*>(&Kr[(size_t)((k0) + sr2) * 32 + sc2]); } while (0)
; #define SWRITE(b, i) do { *(bf16x8*)(V_lds + (b) * SHM_V + vst0) = st_[i].vs; *(bf16x8*)(K_lds + (b) * SHM_K + kst0) = st_[i].ks; \
;     if (DQ == 96) { if (tid < 256) *(bf16x8*)(K_lds + (b) * SHM_K + kst2) = st_[i].kr; } } while (0)
; #define SWAIT() do { if (DQ == 96) asm volatile("s_waitcnt vmcnt(3)" ::: "memory"); else asm volatile("s_waitcnt vmcnt(2)" ::: "memory"); } while (0)
; template <int DQ, bool WIN, int LDQ, int LDK> ...
;     ...
;         SBAR(); qkt<DQ>(pA0, pA1, K_lds, qr, minit, r32, hi);
;         finish(pB0, pB1); SBAR();
;         if (j + 3 < NT) SLOAD(SE, KBASE(j + 3)); SBAR();
;         pv(vb0 + SHM_V);
;         __syncthreads(); SWAIT(); SWRITE(1, SO);
;         lsum_upd();
;         if (WIN) win_mask(pA0, pA1, qrow - KBASE(j + 1), hi);
;         exp16(pA0);
;         __syncthreads();
;     }
;     SBAR(); qkt<DQ>(pB0, pB1, K_lds + SHM_K, qr, minit, r32, hi);
;     finish(pA0, pA1); SBAR();
;     pv(vb0); lsum_upd();
;     if (WIN) win_mask(pB0, pB1, qrow - KBASE(NT - 1), hi);
;     exp16(pB0);
	v_mfma_f32_32x32x16_bf16 v[18:33], v[74:77], v[168:171], v[18:33]
	v_mfma_f32_16x16x32_bf16 v[34:37], v[74:77], v[38:41], v[34:37]
	v_mfma_f32_32x32x16_bf16 v[18:33], v[78:81], v[176:179], v[18:33]
	v_mfma_f32_16x16x32_bf16 v[34:37], v[78:81], v[38:41], v[34:37]
	ds_read_b64_tr_b16 v[42:43], v155 offset:0
	ds_read_b64_tr_b16 v[44:45], v155 offset:0x400
	ds_read_b64_tr_b16 v[46:47], v155 offset:0x800
	ds_read_b64_tr_b16 v[48:49], v155 offset:0xc00
	ds_read_b128 v[66:69], v156 offset:16384
	ds_read_b128 v[160:163], v156 offset:16416
	ds_read_b128 v[164:167], v156 offset:20992
	ds_read_b128 v[168:171], v156 offset:21024
	v_exp_f32_e32 v82, v82
	v_exp_f32_e32 v83, v83
	s_waitcnt lgkmcnt(3)
	v_mfma_f32_32x32x16_bf16 v[98:113], v[66:69], v[126:129], v[50:65]
	v_exp_f32_e32 v84, v84
	v_exp_f32_e32 v85, v85
	v_exp_f32_e32 v89, v89
	v_exp_f32_e32 v196, v91
	v_exp_f32_e32 v197, v96
	v_exp_f32_e32 v198, v97
	s_waitcnt lgkmcnt(1)
	v_mfma_f32_32x32x16_bf16 v[66:81], v[164:167], v[126:129], v[50:65]
	v_mfma_f32_32x32x16_bf16 v[98:113], v[160:163], v[122:125], v[98:113]
	ds_read_b128 v[160:163], v156 offset:16448
	ds_read_b128 v[164:167], v156 offset:16480
	ds_read_b128 v[172:175], v156 offset:21056
	ds_read_b128 v[176:179], v156 offset:21088
	s_waitcnt lgkmcnt(4)
	v_mfma_f32_32x32x16_bf16 v[66:81], v[168:171], v[122:125], v[66:81]
	v_exp_f32_e32 v168, v86
	v_exp_f32_e32 v169, v87
	v_exp_f32_e32 v170, v88
	v_exp_f32_e32 v171, v90
	s_waitcnt lgkmcnt(3)
	v_mfma_f32_32x32x16_bf16 v[98:113], v[160:163], v[118:121], v[98:113]
	v_exp_f32_e32 v160, v92
	v_exp_f32_e32 v161, v93
	v_exp_f32_e32 v162, v94
	v_exp_f32_e32 v163, v95
	v_cvt_pk_bf16_f32 v94, v146, v180
	v_cvt_pk_bf16_f32 v95, v182, v183
	v_cvt_pk_bf16_f32 v96, v184, v185
	s_waitcnt lgkmcnt(1)
	v_mfma_f32_32x32x16_bf16 v[66:81], v[172:175], v[118:121], v[66:81]
	v_cvt_pk_bf16_f32 v97, v186, v187
	v_cvt_pk_bf16_f32 v90, v188, v189
	v_cvt_pk_bf16_f32 v91, v190, v191
	v_cvt_pk_bf16_f32 v92, v192, v193
	v_cvt_pk_bf16_f32 v93, v194, v195
	v_cvt_pk_bf16_f32 v86, v82, v83
	v_cvt_pk_bf16_f32 v87, v84, v85
	v_mfma_f32_32x32x16_bf16 v[98:113], v[164:167], v[114:117], v[98:113]
	v_cvt_pk_bf16_f32 v88, v168, v169
	v_cvt_pk_bf16_f32 v89, v170, v89
	v_cvt_pk_bf16_f32 v82, v171, v196
	v_cvt_pk_bf16_f32 v83, v160, v161
	v_cvt_pk_bf16_f32 v84, v162, v163
	v_cvt_pk_bf16_f32 v85, v197, v198
	s_waitcnt lgkmcnt(0)
	v_mfma_f32_32x32x16_bf16 v[66:81], v[176:179], v[114:117], v[66:81]
	global_load_dwordx4 v[134:137], v[148:149], off
	global_load_dwordx4 v[130:133], v[148:149], off offset:-256
	s_branch .LBB0_492
.LBB0_495:
	s_waitcnt vmcnt(0)
	ds_read_b128 v[98:101], v156 offset:25600
	ds_read_b128 v[102:105], v156 offset:25632
	v_exp_f32_e32 v81, v81
	v_exp_f32_e32 v130, v66
	v_exp_f32_e32 v131, v67
	s_waitcnt lgkmcnt(1)
	v_mfma_f32_32x32x16_bf16 v[82:97], v[98:101], v[126:129], v[50:65]
	ds_read_b128 v[98:101], v156 offset:30208
	ds_read_b128 v[106:109], v156 offset:30240
	v_exp_f32_e32 v132, v68
	s_waitcnt lgkmcnt(1)
	v_mfma_f32_32x32x16_bf16 v[50:65], v[98:101], v[126:129], v[50:65]
	v_mfma_f32_32x32x16_bf16 v[82:97], v[102:105], v[122:125], v[82:97]
	ds_read_b128 v[98:101], v156 offset:25664
	ds_read_b128 v[102:105], v156 offset:25696
	ds_read_b128 v[110:113], v156 offset:30272
	ds_read_b128 v[126:129], v156 offset:30304
	v_cvt_pk_bf16_f32 v66, v138, v139
	v_cvt_pk_bf16_f32 v67, v162, v165
	v_cvt_pk_bf16_f32 v68, v163, v166
	s_waitcnt lgkmcnt(4)
	v_mfma_f32_32x32x16_bf16 v[50:65], v[106:109], v[122:125], v[50:65]
	v_exp_f32_e32 v106, v69
	v_exp_f32_e32 v107, v70
	v_exp_f32_e32 v108, v71
	v_exp_f32_e32 v109, v72
	v_exp_f32_e32 v122, v73
	v_exp_f32_e32 v123, v74
	v_exp_f32_e32 v124, v75
	s_waitcnt lgkmcnt(3)
	v_mfma_f32_32x32x16_bf16 v[82:97], v[98:101], v[118:121], v[82:97]
	v_exp_f32_e32 v98, v76
	v_exp_f32_e32 v99, v77
	v_exp_f32_e32 v100, v78
	v_exp_f32_e32 v101, v79
	v_exp_f32_e32 v125, v80
	v_cvt_pk_bf16_f32 v69, v164, v167
	v_cvt_pk_bf16_f32 v70, v140, v144
	s_waitcnt lgkmcnt(1)
	v_mfma_f32_32x32x16_bf16 v[50:65], v[110:113], v[118:121], v[50:65]
	v_cvt_pk_bf16_f32 v71, v141, v145
	v_cvt_pk_bf16_f32 v72, v142, v160
	v_cvt_pk_bf16_f32 v73, v143, v161
	v_cvt_pk_bf16_f32 v74, v130, v131
	v_cvt_pk_bf16_f32 v75, v132, v106
	v_cvt_pk_bf16_f32 v76, v107, v108
	v_cvt_pk_bf16_f32 v77, v109, v122
	v_mfma_f32_32x32x16_bf16 v[82:97], v[102:105], v[114:117], v[82:97]
	v_cvt_pk_bf16_f32 v78, v123, v124
	v_cvt_pk_bf16_f32 v79, v98, v99
	v_cvt_pk_bf16_f32 v80, v100, v101
	v_cvt_pk_bf16_f32 v81, v125, v81
	s_waitcnt lgkmcnt(0)
	v_mfma_f32_32x32x16_bf16 v[50:65], v[126:129], v[114:117], v[50:65]
	ds_read_b64_tr_b16 v[98:99], v159 offset:0
	ds_read_b64_tr_b16 v[100:101], v159 offset:0x400
	ds_read_b64_tr_b16 v[102:103], v159 offset:0x800
	ds_read_b64_tr_b16 v[104:105], v159 offset:0xc00
	ds_read_b64_tr_b16 v[106:107], v159 offset:0x1000
	ds_read_b64_tr_b16 v[108:109], v159 offset:0x1400
	ds_read_b64_tr_b16 v[110:111], v159 offset:0x1800
	ds_read_b64_tr_b16 v[112:113], v159 offset:0x1c00
	s_waitcnt lgkmcnt(0)
	s_nop 0
	v_mfma_f32_32x32x16_bf16 v[2:17], v[66:69], v[98:101], v[2:17]
	ds_read_b64_tr_b16 v[98:99], v159 offset:0x200
	ds_read_b64_tr_b16 v[100:101], v159 offset:0x600
	v_mfma_f32_32x32x16_bf16 v[2:17], v[70:73], v[102:105], v[2:17]
	ds_read_b64_tr_b16 v[102:103], v159 offset:0xa00
	ds_read_b64_tr_b16 v[104:105], v159 offset:0xe00
	v_mfma_f32_32x32x16_bf16 v[2:17], v[74:77], v[106:109], v[2:17]
	ds_read_b64_tr_b16 v[106:107], v159 offset:0x1200
	ds_read_b64_tr_b16 v[108:109], v159 offset:0x1600
	ds_read_b64_tr_b16 v[114:115], v159 offset:0x1a00
	ds_read_b64_tr_b16 v[116:117], v159 offset:0x1e00
	s_waitcnt lgkmcnt(0)
; #define SBAR() __builtin_amdgcn_sched_barrier(0)
; __device__ __forceinline__ int crow(int r, int hi) { return (r & 3) + 8 * (r >> 2) + 4 * hi; }
; template <int DQ, bool WIN, int LDQ, int LDK> ...
;     ...
;     pv(vb0); lsum_upd();
;     if (WIN) win_mask(pB0, pB1, qrow - KBASE(NT - 1), hi);
;     exp16(pB0);
;     finish(pB0, pB1); SBAR();
;     pv(vb0 + SHM_V); lsum_upd();
;     if (WIN) {
;         if (hi == 0) li_l[r32] = m_ref; asm volatile("s_waitcnt lgkmcnt(0)" ::: "memory");
; #pragma unroll
;         for (int r = 0; r < 16; ++r) lsum[r] += __builtin_amdgcn_exp2f(sink_l2 - li_l[crow(r, hi)]);
;     }
;     float rli[16]; bool fin = true;
; #pragma unroll
;     for (int r = 0; r < 16; ++r) { fin = fin && (lsum[r] < ATT_GUARD) && (lsum[r] > 0.f); rli[r] = __builtin_amdgcn_rcpf(lsum[r]); }
;     if (!__all(fin)) { if (lane == 0) *redo_flag = 1; }
	v_mfma_f32_32x32x16_bf16 v[2:17], v[78:81], v[110:113], v[2:17]
	v_mfma_f32_32x32x16_bf16 v[18:33], v[66:69], v[98:101], v[18:33]
	v_mov_b64_e32 v[100:101], s[14:15]
	v_mov_b64_e32 v[98:99], s[12:13]
	s_nop 3
	v_exp_f32_e32 v65, v65
	v_exp_f32_e32 v82, v82
	v_exp_f32_e32 v83, v83
	v_exp_f32_e32 v84, v84
	v_exp_f32_e32 v85, v85
	v_mfma_f32_16x16x32_bf16 v[34:37], v[66:69], v[38:41], v[34:37]
	v_exp_f32_e32 v86, v86
	v_exp_f32_e32 v87, v87
	v_exp_f32_e32 v88, v88
	v_exp_f32_e32 v89, v89
	v_exp_f32_e32 v90, v90
	v_exp_f32_e32 v91, v91
	v_exp_f32_e32 v92, v92
	v_mfma_f32_32x32x16_bf16 v[18:33], v[70:73], v[102:105], v[18:33]
	v_exp_f32_e32 v93, v93
	v_exp_f32_e32 v94, v94
	v_exp_f32_e32 v95, v95
	v_exp_f32_e32 v96, v96
	v_exp_f32_e32 v97, v97
	v_exp_f32_e32 v102, v50
	v_exp_f32_e32 v103, v51
	v_mfma_f32_16x16x32_bf16 v[34:37], v[70:73], v[38:41], v[34:37]
	v_exp_f32_e32 v104, v52
	v_exp_f32_e32 v105, v53
	v_exp_f32_e32 v110, v58
	v_exp_f32_e32 v111, v59
	v_exp_f32_e32 v66, v60
	v_exp_f32_e32 v67, v61
	v_exp_f32_e32 v68, v62
	v_mfma_f32_32x32x16_bf16 v[18:33], v[74:77], v[106:109], v[18:33]
	v_exp_f32_e32 v106, v54
	v_exp_f32_e32 v107, v55
	v_exp_f32_e32 v108, v56
	v_exp_f32_e32 v109, v57
	v_exp_f32_e32 v69, v63
	v_exp_f32_e32 v112, v64
	v_cvt_pk_bf16_f32 v50, v82, v83
	v_mfma_f32_16x16x32_bf16 v[34:37], v[74:77], v[38:41], v[34:37]
	v_cvt_pk_bf16_f32 v51, v84, v85
	v_cvt_pk_bf16_f32 v52, v86, v87
	v_cvt_pk_bf16_f32 v53, v88, v89
	v_cvt_pk_bf16_f32 v54, v90, v91
	v_cvt_pk_bf16_f32 v55, v92, v93
	v_cvt_pk_bf16_f32 v56, v94, v95
	v_cvt_pk_bf16_f32 v57, v96, v97
	v_mfma_f32_32x32x16_bf16 v[18:33], v[78:81], v[114:117], v[18:33]
	v_cvt_pk_bf16_f32 v58, v102, v103
	v_cvt_pk_bf16_f32 v59, v104, v105
	v_cvt_pk_bf16_f32 v60, v106, v107
	v_cvt_pk_bf16_f32 v61, v108, v109
	v_cvt_pk_bf16_f32 v62, v110, v111
	v_cvt_pk_bf16_f32 v63, v66, v67
	v_cvt_pk_bf16_f32 v64, v68, v69
	v_mfma_f32_16x16x32_bf16 v[34:37], v[78:81], v[38:41], v[34:37]
	v_cvt_pk_bf16_f32 v65, v112, v65
	ds_read_b64_tr_b16 v[66:67], v155 offset:0
	ds_read_b64_tr_b16 v[68:69], v155 offset:0x400
	ds_read_b64_tr_b16 v[70:71], v155 offset:0x800
	ds_read_b64_tr_b16 v[72:73], v155 offset:0xc00
	ds_read_b64_tr_b16 v[74:75], v155 offset:0x1000
	ds_read_b64_tr_b16 v[76:77], v155 offset:0x1400
	ds_read_b64_tr_b16 v[78:79], v155 offset:0x1800
	ds_read_b64_tr_b16 v[80:81], v155 offset:0x1c00
	s_waitcnt lgkmcnt(0)
	s_nop 0
	v_mfma_f32_32x32x16_bf16 v[2:17], v[50:53], v[66:69], v[2:17]
	ds_read_b64_tr_b16 v[66:67], v155 offset:0x200
	ds_read_b64_tr_b16 v[68:69], v155 offset:0x600
	v_mfma_f32_32x32x16_bf16 v[2:17], v[54:57], v[70:73], v[2:17]
	ds_read_b64_tr_b16 v[70:71], v155 offset:0xa00
	ds_read_b64_tr_b16 v[72:73], v155 offset:0xe00
	v_mfma_f32_32x32x16_bf16 v[2:17], v[58:61], v[74:77], v[2:17]
	ds_read_b64_tr_b16 v[74:75], v155 offset:0x1200
	ds_read_b64_tr_b16 v[76:77], v155 offset:0x1600
	ds_read_b64_tr_b16 v[82:83], v155 offset:0x1a00
	ds_read_b64_tr_b16 v[84:85], v155 offset:0x1e00
	s_waitcnt lgkmcnt(0)
	v_mfma_f32_32x32x16_bf16 v[2:17], v[62:65], v[78:81], v[2:17]
	v_mfma_f32_16x16x32_bf16 v[34:37], v[50:53], v[38:41], v[34:37]
	v_mfma_f32_16x16x32_bf16 v[34:37], v[54:57], v[38:41], v[34:37]
	v_mfma_f32_16x16x32_bf16 v[34:37], v[58:61], v[38:41], v[34:37]
	v_mfma_f32_16x16x32_bf16 v[34:37], v[62:65], v[38:41], v[34:37]
	v_mfma_f32_32x32x16_bf16 v[18:33], v[50:53], v[66:69], v[18:33]
	v_lshrrev_b32_e32 v98, 4, v151
	v_and_b32_e32 v99, 1, v151
	v_lshlrev_b32_e32 v98, 4, v98
	v_lshl_or_b32 v98, v99, 6, v98
	s_lshl_b32 s0, s20, 3
	s_add_i32 s0, s0, 0x8800
	v_add_u32_e32 v98, s0, v98
	v_lshl_add_u32 v99, v1, 4, s0
	s_nop 1
	ds_write_b128 v98, v[34:37]
	s_waitcnt lgkmcnt(0)
	ds_read_b128 v[34:37], v99
	ds_read_b128 v[38:41], v99 offset:32
	ds_read_b128 v[42:45], v99 offset:64
	ds_read_b128 v[46:49], v99 offset:96
	s_waitcnt lgkmcnt(0)
	v_cmp_gt_f32_e32 vcc, s88, v34
	v_cmp_lt_f32_e64 s[0:1], 0, v34
	s_and_b64 s[22:23], vcc, s[0:1]
	v_cmp_gt_f32_e32 vcc, s88, v35
	v_cmp_lt_f32_e64 s[0:1], 0, v35
	s_and_b64 s[0:1], vcc, s[0:1]
	s_and_b64 s[22:23], s[22:23], s[0:1]
	v_cmp_gt_f32_e32 vcc, s88, v36
	v_cmp_lt_f32_e64 s[0:1], 0, v36
	s_and_b64 s[0:1], vcc, s[0:1]
	s_and_b64 s[22:23], s[22:23], s[0:1]
	v_cmp_gt_f32_e32 vcc, s88, v37
	v_cmp_lt_f32_e64 s[0:1], 0, v37
	s_and_b64 s[0:1], vcc, s[0:1]
	s_and_b64 s[22:23], s[22:23], s[0:1]
	v_cmp_gt_f32_e32 vcc, s88, v38
	v_cmp_lt_f32_e64 s[0:1], 0, v38
	s_and_b64 s[0:1], vcc, s[0:1]
	s_and_b64 s[22:23], s[22:23], s[0:1]
	v_cmp_gt_f32_e32 vcc, s88, v39
	v_cmp_lt_f32_e64 s[0:1], 0, v39
	s_and_b64 s[0:1], vcc, s[0:1]
	s_and_b64 s[22:23], s[22:23], s[0:1]
	v_cmp_gt_f32_e32 vcc, s88, v40
	v_cmp_lt_f32_e64 s[0:1], 0, v40
	s_and_b64 s[0:1], vcc, s[0:1]
	s_and_b64 s[22:23], s[22:23], s[0:1]
	v_cmp_gt_f32_e32 vcc, s88, v41
	v_cmp_lt_f32_e64 s[0:1], 0, v41
	s_and_b64 s[0:1], vcc, s[0:1]
	v_mfma_f32_32x32x16_bf16 v[18:33], v[54:57], v[70:73], v[18:33]
	s_and_b64 s[22:23], s[22:23], s[0:1]
	v_cmp_gt_f32_e32 vcc, s88, v42
	v_cmp_lt_f32_e64 s[0:1], 0, v42
	s_and_b64 s[0:1], vcc, s[0:1]
	s_and_b64 s[22:23], s[22:23], s[0:1]
	v_cmp_gt_f32_e32 vcc, s88, v43
	v_cmp_lt_f32_e64 s[0:1], 0, v43
	s_and_b64 s[0:1], vcc, s[0:1]
	s_and_b64 s[22:23], s[22:23], s[0:1]
	v_cmp_gt_f32_e32 vcc, s88, v44
	v_cmp_lt_f32_e64 s[0:1], 0, v44
	s_and_b64 s[0:1], vcc, s[0:1]
	s_and_b64 s[22:23], s[22:23], s[0:1]
	v_cmp_gt_f32_e32 vcc, s88, v45
	v_cmp_lt_f32_e64 s[0:1], 0, v45
	s_and_b64 s[0:1], vcc, s[0:1]
	v_mfma_f32_32x32x16_bf16 v[18:33], v[58:61], v[74:77], v[18:33]
	s_and_b64 s[22:23], s[22:23], s[0:1]
	v_cmp_gt_f32_e32 vcc, s88, v46
	v_cmp_lt_f32_e64 s[0:1], 0, v46
	s_and_b64 s[0:1], vcc, s[0:1]
	s_and_b64 s[22:23], s[22:23], s[0:1]
	v_cmp_gt_f32_e32 vcc, s88, v47
	v_cmp_lt_f32_e64 s[0:1], 0, v47
	s_and_b64 s[0:1], vcc, s[0:1]
	s_and_b64 s[22:23], s[22:23], s[0:1]
	v_cmp_gt_f32_e32 vcc, s88, v48
	v_cmp_lt_f32_e64 s[0:1], 0, v48
	s_and_b64 s[0:1], vcc, s[0:1]
	s_and_b64 s[22:23], s[22:23], s[0:1]
	v_cmp_gt_f32_e32 vcc, s88, v49
	v_cmp_lt_f32_e64 s[0:1], 0, v49
	s_and_b64 s[0:1], vcc, s[0:1]
	v_mfma_f32_32x32x16_bf16 v[18:33], v[62:65], v[82:85], v[18:33]
	s_and_b64 s[0:1], s[22:23], s[0:1]
	v_cndmask_b32_e64 v50, 0, 1, s[0:1]
	v_cmp_ne_u32_e32 vcc, 0, v50
	s_cmp_eq_u64 vcc, exec
	s_cselect_b64 s[0:1], -1, 0
	v_cndmask_b32_e64 v50, 0, 1, s[0:1]
	v_or_b32_e32 v50, v151, v50
	v_cmp_eq_u32_e32 vcc, 0, v50
	s_and_saveexec_b64 s[0:1], vcc
	s_cbranch_execz .LBB0_497
	s_mov_b64 s[22:23], src_shared_base
	s_cmp_lg_u32 s97, -1
	s_cselect_b32 s21, s97, 0
	s_cselect_b32 s22, s23, 0
	v_mov_b32_e32 v50, s21
	v_mov_b32_e32 v51, s22
	flat_store_dword v[50:51], v152 sc0 sc1
	s_waitcnt vmcnt(0)

; #define SBAR() __builtin_amdgcn_sched_barrier(0)
; #define SLOAD(i, k0) do { st_[i].vs = *reinterpret_cast<const bf16x8*>(&Vh[(size_t)((k0) + sr) * LDK + sc]); \
;     st_[i].ks = *reinterpret_cast<const bf16x8*>(&Kh[(size_t)((k0) + sr) * LDK + sc]); \
;     if (DQ == 96) st_[i].kr = *reinterpret_cast<const bf16x8*>(&Kr[(size_t)((k0) + sr2) * 32 + sc2]); } while (0)
; #define SWRITE(b, i) do { *(bf16x8*)(V_lds + (b) * SHM_V + vst0) = st_[i].vs; *(bf16x8*)(K_lds + (b) * SHM_K + kst0) = st_[i].ks; \
;     if (DQ == 96) { if (tid < 256) *(bf16x8*)(K_lds + (b) * SHM_K + kst2) = st_[i].kr; } } while (0)
; #define SWAIT() do { if (DQ == 96) asm volatile("s_waitcnt vmcnt(3)" ::: "memory"); else asm volatile("s_waitcnt vmcnt(2)" ::: "memory"); } while (0)
; #define SLOAD(i, k0) do { st_[i].vs = *reinterpret_cast<const bf16x8*>(&Vh[(size_t)((k0) + sr) * LDK + sc]); \
;     st_[i].ks = *reinterpret_cast<const bf16x8*>(&Kh[(size_t)((k0) + sr) * LDK + sc]); \
;     if (DQ == 96) st_[i].kr = *reinterpret_cast<const bf16x8*>(&Kr[(size_t)((k0) + sr2) * 32 + sc2]); } while (0)
; #define SWRITE(b, i) do { *(bf16x8*)(V_lds + (b) * SHM_V + vst0) = st_[i].vs; *(bf16x8*)(K_lds + (b) * SHM_K + kst0) = st_[i].ks; \
;     if (DQ == 96) { if (tid < 256) *(bf16x8*)(K_lds + (b) * SHM_K + kst2) = st_[i].kr; } } while (0)
; #define SWAIT() do { if (DQ == 96) asm volatile("s_waitcnt vmcnt(3)" ::: "memory"); else asm volatile("s_waitcnt vmcnt(2)" ::: "memory"); } while (0)
; template <int DQ, bool WIN, int LDQ, int LDK> ...
;     ...
;         SBAR(); qkt<DQ>(pB0, pB1, K_lds + SHM_K, qr, minit, r32, hi);
;         finish(pA0, pA1); SBAR();
;         SLOAD(SO, KBASE(j + 2)); SBAR();
;         pv(vb0);
;         __syncthreads(); SWAIT(); SWRITE(0, SE);
;         lsum_upd();
.LBB0_1094:
	ds_read_b64_tr_b16 v[40:41], v194 offset:0
	ds_read_b64_tr_b16 v[42:43], v194 offset:0x400
	ds_read_b64_tr_b16 v[44:45], v194 offset:0x800
	ds_read_b64_tr_b16 v[46:47], v194 offset:0xc00
	ds_read_b128 v[198:201], v191 offset:36352
	ds_read_b128 v[80:83], v191 offset:29696
	ds_read_b128 v[202:205], v191 offset:29728
	v_exp_f32_e32 v72, v72
	v_exp_f32_e32 v73, v73
	v_exp_f32_e32 v74, v74
	s_waitcnt lgkmcnt(1)
	v_mfma_f32_32x32x16_bf16 v[96:111], v[80:83], v[134:137], v[48:63]
	v_exp_f32_e32 v75, v75
	v_exp_f32_e32 v197, v64
	v_exp_f32_e32 v206, v77
	v_exp_f32_e32 v207, v78
	v_exp_f32_e32 v208, v79
	v_mfma_f32_32x32x16_bf16 v[80:95], v[198:201], v[134:137], v[48:63]
	ds_read_b128 v[198:201], v191 offset:36384
	s_waitcnt lgkmcnt(1)
	v_mfma_f32_32x32x16_bf16 v[96:111], v[202:205], v[130:133], v[96:111]
	s_waitcnt lgkmcnt(0)
	v_mfma_f32_32x32x16_bf16 v[80:95], v[198:201], v[130:133], v[80:95]
	ds_read_b128 v[198:201], v191 offset:29760
	ds_read_b128 v[202:205], v191 offset:36416
	s_waitcnt lgkmcnt(1)
	v_mfma_f32_32x32x16_bf16 v[96:111], v[198:201], v[126:129], v[96:111]
	s_waitcnt lgkmcnt(0)
	v_mfma_f32_32x32x16_bf16 v[80:95], v[202:205], v[126:129], v[80:95]
	ds_read_b128 v[198:201], v191 offset:29792
	ds_read_b128 v[202:205], v191 offset:36448
	s_waitcnt lgkmcnt(1)
	v_mfma_f32_32x32x16_bf16 v[96:111], v[198:201], v[122:125], v[96:111]
	s_waitcnt lgkmcnt(0)
	v_mfma_f32_32x32x16_bf16 v[80:95], v[202:205], v[122:125], v[80:95]
	ds_read_b128 v[198:201], v191 offset:29824
	ds_read_b128 v[202:205], v191 offset:36480
	s_waitcnt lgkmcnt(1)
	v_mfma_f32_32x32x16_bf16 v[96:111], v[198:201], v[118:121], v[96:111]
	s_waitcnt lgkmcnt(0)
	v_mfma_f32_32x32x16_bf16 v[80:95], v[202:205], v[118:121], v[80:95]
	ds_read_b128 v[198:201], v191 offset:29856
	ds_read_b128 v[202:205], v191 offset:36512
	s_waitcnt lgkmcnt(1)
	v_mfma_f32_32x32x16_bf16 v[96:111], v[198:201], v[114:117], v[96:111]
	v_exp_f32_e32 v198, v65
	v_exp_f32_e32 v199, v66
	v_exp_f32_e32 v200, v67
	v_exp_f32_e32 v201, v68
	v_cvt_pk_bf16_f32 v68, v161, v196
	s_waitcnt lgkmcnt(0)
	v_mfma_f32_32x32x16_bf16 v[80:95], v[202:205], v[114:117], v[80:95]
	v_exp_f32_e32 v202, v69
	v_exp_f32_e32 v203, v70
	v_exp_f32_e32 v204, v71
	v_exp_f32_e32 v205, v76
	v_cvt_pk_bf16_f32 v69, v158, v168
	v_cvt_pk_bf16_f32 v70, v159, v169
	v_cvt_pk_bf16_f32 v71, v160, v195
	v_cvt_pk_bf16_f32 v64, v150, v154
	v_cvt_pk_bf16_f32 v65, v151, v155
	v_cvt_pk_bf16_f32 v66, v152, v156
	v_cvt_pk_bf16_f32 v67, v153, v157
	v_cvt_pk_bf16_f32 v76, v197, v198
	v_cvt_pk_bf16_f32 v77, v199, v200
	v_cvt_pk_bf16_f32 v78, v201, v202
	v_cvt_pk_bf16_f32 v79, v203, v204
	v_cvt_pk_bf16_f32 v72, v72, v73
	v_cvt_pk_bf16_f32 v73, v74, v75
	v_cvt_pk_bf16_f32 v74, v205, v206
	v_cvt_pk_bf16_f32 v75, v207, v208
	v_lshl_add_u64 v[168:169], s[26:27], 0, v[164:165]
	s_mov_b32 s4, 0x218c0000
	v_add_co_u32_e32 v150, vcc, s4, v168
	s_nop 1
	v_addc_co_u32_e32 v151, vcc, 0, v169, vcc
	global_load_dwordx4 v[154:157], v[150:151], off offset:128
	global_load_dwordx4 v[158:161], v[150:151], off
	v_lshl_add_u64 v[150:151], s[26:27], 0, v[166:167]
	global_load_dwordx4 v[150:153], v[150:151], off
	ds_read_b64_tr_b16 v[204:205], v194 offset:0x1000
	ds_read_b64_tr_b16 v[206:207], v194 offset:0x1400
	ds_read_b64_tr_b16 v[208:209], v194 offset:0x1800
	ds_read_b64_tr_b16 v[210:211], v194 offset:0x1c00
	ds_read_b64_tr_b16 v[196:197], v194 offset:0x200
	ds_read_b64_tr_b16 v[198:199], v194 offset:0x600
	ds_read_b64_tr_b16 v[200:201], v194 offset:0xa00
	ds_read_b64_tr_b16 v[202:203], v194 offset:0xe00
	v_mfma_f32_32x32x16_bf16 v[0:15], v[68:71], v[40:43], v[0:15]
	v_mfma_f32_32x32x16_bf16 v[0:15], v[64:67], v[44:47], v[0:15]
	s_waitcnt lgkmcnt(6)
	v_mfma_f32_32x32x16_bf16 v[0:15], v[76:79], v[204:207], v[0:15]
	ds_read_b64_tr_b16 v[204:205], v194 offset:0x1200
	ds_read_b64_tr_b16 v[206:207], v194 offset:0x1600
	s_waitcnt lgkmcnt(6)
	v_mfma_f32_32x32x16_bf16 v[0:15], v[72:75], v[208:211], v[0:15]
	ds_read_b64_tr_b16 v[208:209], v194 offset:0x1a00
	ds_read_b64_tr_b16 v[210:211], v194 offset:0x1e00
	s_waitcnt lgkmcnt(0)
	v_mfma_f32_32x32x16_bf16 v[16:31], v[68:71], v[196:199], v[16:31]
	s_waitcnt vmcnt(3)
	ds_write_b128 v192, v[138:141]
	ds_write_b128 v193, v[142:145] offset:16384
	v_mfma_f32_32x32x16_bf16 v[16:31], v[64:67], v[200:203], v[16:31]
	v_mfma_f32_32x32x16_bf16 v[16:31], v[76:79], v[204:207], v[16:31]
	v_mfma_f32_32x32x16_bf16 v[16:31], v[72:75], v[208:211], v[16:31]
	ds_write_b128 v112, v[146:149] offset:16512

; #define SBAR() __builtin_amdgcn_sched_barrier(0)
; #define SLOAD(i, k0) do { st_[i].vs = *reinterpret_cast<const bf16x8*>(&Vh[(size_t)((k0) + sr) * LDK + sc]); \
;     st_[i].ks = *reinterpret_cast<const bf16x8*>(&Kh[(size_t)((k0) + sr) * LDK + sc]); \
;     if (DQ == 96) st_[i].kr = *reinterpret_cast<const bf16x8*>(&Kr[(size_t)((k0) + sr2) * 32 + sc2]); } while (0)
; #define SWRITE(b, i) do { *(bf16x8*)(V_lds + (b) * SHM_V + vst0) = st_[i].vs; *(bf16x8*)(K_lds + (b) * SHM_K + kst0) = st_[i].ks; \
;     if (DQ == 96) { if (tid < 256) *(bf16x8*)(K_lds + (b) * SHM_K + kst2) = st_[i].kr; } } while (0)
; #define SWAIT() do { if (DQ == 96) asm volatile("s_waitcnt vmcnt(3)" ::: "memory"); else asm volatile("s_waitcnt vmcnt(2)" ::: "memory"); } while (0)
; #define SLOAD(i, k0) do { st_[i].vs = *reinterpret_cast<const bf16x8*>(&Vh[(size_t)((k0) + sr) * LDK + sc]); \
;     st_[i].ks = *reinterpret_cast<const bf16x8*>(&Kh[(size_t)((k0) + sr) * LDK + sc]); \
;     if (DQ == 96) st_[i].kr = *reinterpret_cast<const bf16x8*>(&Kr[(size_t)((k0) + sr2) * 32 + sc2]); } while (0)
; #define SWRITE(b, i) do { *(bf16x8*)(V_lds + (b) * SHM_V + vst0) = st_[i].vs; *(bf16x8*)(K_lds + (b) * SHM_K + kst0) = st_[i].ks; \
;     if (DQ == 96) { if (tid < 256) *(bf16x8*)(K_lds + (b) * SHM_K + kst2) = st_[i].kr; } } while (0)
; #define SWAIT() do { if (DQ == 96) asm volatile("s_waitcnt vmcnt(3)" ::: "memory"); else asm volatile("s_waitcnt vmcnt(2)" ::: "memory"); } while (0)
; template <int DQ, bool WIN, int LDQ, int LDK> ...
;     ...
;         if (j + 3 < NT) SLOAD(SE, KBASE(j + 3)); SBAR();
;         pv(vb0 + SHM_V);
;         __syncthreads(); SWAIT(); SWRITE(1, SO);
;         lsum_upd();
.LBB0_1098:
	ds_read_b64_tr_b16 v[204:205], v190 offset:0x1000
	ds_read_b64_tr_b16 v[206:207], v190 offset:0x1400
	ds_read_b64_tr_b16 v[208:209], v190 offset:0x1800
	ds_read_b64_tr_b16 v[210:211], v190 offset:0x1c00
	ds_read_b64_tr_b16 v[196:197], v190 offset:0x200
	ds_read_b64_tr_b16 v[198:199], v190 offset:0x600
	ds_read_b64_tr_b16 v[200:201], v190 offset:0xa00
	ds_read_b64_tr_b16 v[202:203], v190 offset:0xe00
	v_mfma_f32_32x32x16_bf16 v[0:15], v[80:83], v[40:43], v[0:15]
	v_mfma_f32_32x32x16_bf16 v[0:15], v[84:87], v[44:47], v[0:15]
	s_waitcnt lgkmcnt(6)
	v_mfma_f32_32x32x16_bf16 v[0:15], v[88:91], v[204:207], v[0:15]
	ds_read_b64_tr_b16 v[204:205], v190 offset:0x1200
	ds_read_b64_tr_b16 v[206:207], v190 offset:0x1600
	s_waitcnt lgkmcnt(6)
	v_mfma_f32_32x32x16_bf16 v[0:15], v[92:95], v[208:211], v[0:15]
	ds_read_b64_tr_b16 v[208:209], v190 offset:0x1a00
	ds_read_b64_tr_b16 v[210:211], v190 offset:0x1e00
	s_waitcnt lgkmcnt(0)
	v_mfma_f32_32x32x16_bf16 v[16:31], v[80:83], v[196:199], v[16:31]
	s_waitcnt vmcnt(3)
	ds_write_b128 v192, v[154:157] offset:8192
	ds_write_b128 v193, v[158:161] offset:29696
	v_mfma_f32_32x32x16_bf16 v[16:31], v[84:87], v[200:203], v[16:31]
	v_mfma_f32_32x32x16_bf16 v[16:31], v[88:91], v[204:207], v[16:31]
	v_mfma_f32_32x32x16_bf16 v[16:31], v[92:95], v[208:211], v[16:31]
	ds_write_b128 v112, v[150:153] offset:29824
	s_branch .LBB0_1093
